# v58 + all individually validated neutral refinements stacked: unrolled small_gemm read pipelining, stash read batching, residual s_nop cleanup, pipelined final RMSNorm loop, exact small_gemm prefetch-
# baseline (speedup 1.0000x reference)
.LBB0_456:
	s_cmp_gt_u32 s7, 12
	ds_read_b128 v[102:105], v78 offset:18432
	ds_read_b128 v[106:109], v80
	ds_read_b128 v[110:113], v78 offset:20736
	ds_read_b128 v[114:117], v78 offset:23040
	ds_read_b128 v[118:121], v78 offset:25344
	ds_read_b128 v[122:125], v78 offset:29952
	ds_read_b128 v[126:129], v78 offset:34560
	s_waitcnt lgkmcnt(5)
	v_mfma_f32_16x16x32_bf16 v[64:67], v[102:105], v[106:109], v[64:67]
	ds_read_b128 v[102:105], v78 offset:27648
	s_waitcnt lgkmcnt(5)
	v_mfma_f32_16x16x32_bf16 v[28:31], v[110:113], v[106:109], v[28:31]
	ds_read_b128 v[110:113], v78 offset:32256
	ds_read_b128 v[130:133], v78 offset:18496
	s_waitcnt lgkmcnt(5)
	v_mfma_f32_16x16x32_bf16 v[20:23], v[118:121], v[106:109], v[20:23]
	ds_read_b128 v[98:101], v80 offset:64
	s_waitcnt lgkmcnt(5)
	v_mfma_f32_16x16x32_bf16 v[90:93], v[122:125], v[106:109], v[12:15]
	s_waitcnt lgkmcnt(7)
	v_mfma_f32_16x16x32_bf16 v[24:27], v[114:117], v[106:109], v[24:27]
	ds_read_b128 v[114:117], v78 offset:23104
	ds_read_b128 v[118:121], v78 offset:20800
	s_waitcnt lgkmcnt(5)
	v_mfma_f32_16x16x32_bf16 v[82:85], v[102:105], v[106:109], v[16:19]
	ds_read_b128 v[102:105], v78 offset:25408
	s_waitcnt lgkmcnt(5)
	v_mfma_f32_16x16x32_bf16 v[94:97], v[110:113], v[106:109], v[8:11]
	s_waitcnt lgkmcnt(7)
	v_mfma_f32_16x16x32_bf16 v[4:7], v[126:129], v[106:109], v[4:7]
	ds_read_b128 v[106:109], v78 offset:27712
	s_waitcnt lgkmcnt(2)
	v_mfma_f32_16x16x32_bf16 v[12:15], v[118:121], v[98:101], v[28:31]
	s_nop 2
	ds_read_b128 v[28:31], v78 offset:30016
	s_waitcnt lgkmcnt(4)
	v_mfma_f32_16x16x32_bf16 v[16:19], v[114:117], v[98:101], v[24:27]
	s_waitcnt lgkmcnt(2)
	v_mfma_f32_16x16x32_bf16 v[20:23], v[102:105], v[98:101], v[20:23]
	s_waitcnt lgkmcnt(5)
	v_mfma_f32_16x16x32_bf16 v[8:11], v[130:133], v[98:101], v[64:67]
	s_waitcnt lgkmcnt(1)
	v_mfma_f32_16x16x32_bf16 v[24:27], v[106:109], v[98:101], v[82:85]
	s_waitcnt lgkmcnt(1)
	s_nop 0
	ds_read_b128 v[64:67], v78 offset:32320
	s_nop 0
	ds_read_b128 v[82:85], v78 offset:34624
	s_and_b64 vcc, exec, s[0:1]
	s_cbranch_vccnz .Lsgl_old_0
	s_waitcnt vmcnt(4)
	ds_write_b128 v81, v[40:43] offset:36864
	ds_write_b128 v81, v[44:47] offset:46080
	ds_write_b128 v81, v[56:59] offset:55296
	ds_write_b128 v81, v[60:63] offset:64512
	s_branch .Lsgl_join_0
.Lsgl_old_0:
	s_waitcnt vmcnt(3)
	ds_write_b128 v81, v[40:43] offset:36864
	s_waitcnt vmcnt(2)
	ds_write_b128 v81, v[44:47] offset:46080
	s_waitcnt vmcnt(1)
	ds_write_b128 v81, v[56:59] offset:55296
	s_waitcnt vmcnt(0)
	ds_write_b128 v81, v[60:63] offset:64512
.Lsgl_join_0:
	s_cmp_gt_u32 s7, 12
	s_waitcnt lgkmcnt(6)
	v_mfma_f32_16x16x32_bf16 v[28:31], v[28:31], v[98:101], v[90:93]
	s_waitcnt lgkmcnt(0)
	s_barrier
	s_waitcnt lgkmcnt(5)
	v_mfma_f32_16x16x32_bf16 v[64:67], v[64:67], v[98:101], v[94:97]
	s_waitcnt lgkmcnt(4)
	v_mfma_f32_16x16x32_bf16 v[4:7], v[82:85], v[98:101], v[4:7]
	s_cbranch_scc1 .LBB0_458
	v_add_co_u32_e32 v40, vcc, 0x11400000, v76
	s_nop 1
	v_addc_co_u32_e32 v41, vcc, 0, v77, vcc
	v_add_co_u32_e32 v44, vcc, 0x11420000, v76
	s_nop 1
	v_addc_co_u32_e32 v45, vcc, 0, v77, vcc
	v_add_co_u32_e32 v56, vcc, 0x400000, v74
	global_load_dwordx4 v[40:43], v[40:41], off offset:384
	s_nop 0
	global_load_dwordx4 v[44:47], v[44:45], off offset:384
	v_addc_co_u32_e32 v57, vcc, 0, v75, vcc
	v_add_co_u32_e32 v60, vcc, 0x420000, v74
	s_nop 1
	v_addc_co_u32_e32 v61, vcc, 0, v75, vcc
	global_load_dwordx4 v[56:59], v[56:57], off offset:384
	s_nop 0
	global_load_dwordx4 v[60:63], v[60:61], off offset:384
.LBB0_458:
	s_andn2_b64 vcc, exec, s[4:5]
	ds_read_b128 v[98:101], v78 offset:55296
	ds_read_b128 v[102:105], v80 offset:36864
	ds_read_b128 v[106:109], v78 offset:57600
	ds_read_b128 v[110:113], v78 offset:59904
	ds_read_b128 v[114:117], v78 offset:62208
	ds_read_b128 v[118:121], v78 offset:64512
	ds_read_b128 v[122:125], v79 offset:11520
	s_waitcnt lgkmcnt(5)
	v_mfma_f32_16x16x32_bf16 v[8:11], v[98:101], v[102:105], v[8:11]
	ds_read_b128 v[98:101], v79 offset:13824
	s_waitcnt lgkmcnt(5)
	v_mfma_f32_16x16x32_bf16 v[12:15], v[106:109], v[102:105], v[12:15]
	ds_read_b128 v[106:109], v79 offset:16128
	s_waitcnt lgkmcnt(5)
	v_mfma_f32_16x16x32_bf16 v[16:19], v[110:113], v[102:105], v[16:19]
	ds_read_b128 v[110:113], v78 offset:55360
	s_waitcnt lgkmcnt(5)
	v_mfma_f32_16x16x32_bf16 v[20:23], v[114:117], v[102:105], v[20:23]
	ds_read_b128 v[114:117], v80 offset:36928
	s_waitcnt lgkmcnt(5)
	v_mfma_f32_16x16x32_bf16 v[74:77], v[118:121], v[102:105], v[24:27]
	ds_read_b128 v[118:121], v78 offset:57664
	s_waitcnt lgkmcnt(5)
	v_mfma_f32_16x16x32_bf16 v[86:89], v[122:125], v[102:105], v[28:31]
	ds_read_b128 v[122:125], v78 offset:59968
	s_waitcnt lgkmcnt(5)
	v_mfma_f32_16x16x32_bf16 v[90:93], v[98:101], v[102:105], v[64:67]
	ds_read_b128 v[98:101], v78 offset:62272
	s_waitcnt lgkmcnt(5)
	v_mfma_f32_16x16x32_bf16 v[4:7], v[106:109], v[102:105], v[4:7]
	ds_read_b128 v[102:105], v78 offset:64576
	ds_read_b128 v[106:109], v79 offset:11584
	s_waitcnt lgkmcnt(5)
	v_mfma_f32_16x16x32_bf16 v[64:67], v[110:113], v[114:117], v[8:11]
	ds_read_b128 v[110:113], v79 offset:13888
	s_waitcnt lgkmcnt(5)
	v_mfma_f32_16x16x32_bf16 v[28:31], v[118:121], v[114:117], v[12:15]
	ds_read_b128 v[118:121], v79 offset:16192
	s_waitcnt lgkmcnt(5)
	v_mfma_f32_16x16x32_bf16 v[24:27], v[122:125], v[114:117], v[16:19]
	s_waitcnt lgkmcnt(4)
	v_mfma_f32_16x16x32_bf16 v[20:23], v[98:101], v[114:117], v[20:23]
	s_waitcnt lgkmcnt(3)
	v_mfma_f32_16x16x32_bf16 v[16:19], v[102:105], v[114:117], v[74:77]
	s_waitcnt lgkmcnt(2)
	v_mfma_f32_16x16x32_bf16 v[12:15], v[106:109], v[114:117], v[86:89]
	s_waitcnt lgkmcnt(1)
	v_mfma_f32_16x16x32_bf16 v[8:11], v[110:113], v[114:117], v[90:93]
	s_waitcnt lgkmcnt(0)
	v_mfma_f32_16x16x32_bf16 v[4:7], v[118:121], v[114:117], v[4:7]
	s_waitcnt lgkmcnt(0)
	s_cbranch_vccnz .LBB0_453
	s_waitcnt vmcnt(4)
	ds_write_b128 v81, v[32:35]
	ds_write_b128 v81, v[36:39] offset:9216
	ds_write_b128 v81, v[48:51] offset:18432
	ds_write_b128 v81, v[52:55] offset:27648
	s_branch .LBB0_453

.LBB0_904:
	s_cmp_gt_u32 s8, 12
	ds_read_b128 v[148:151], v80
	ds_read_b128 v[152:155], v78 offset:18432
	ds_read_b128 v[156:159], v78 offset:20736
	ds_read_b128 v[160:163], v78 offset:23040
	ds_read_b128 v[164:167], v78 offset:25344
	ds_read_b128 v[168:171], v78 offset:27648
	ds_read_b128 v[172:175], v78 offset:29952
	s_waitcnt lgkmcnt(5)
	v_mfma_f32_16x16x32_bf16 v[64:67], v[152:155], v[148:151], v[64:67]
	ds_read_b128 v[152:155], v78 offset:32256
	s_waitcnt lgkmcnt(5)
	v_mfma_f32_16x16x32_bf16 v[28:31], v[156:159], v[148:151], v[28:31]
	ds_read_b128 v[156:159], v78 offset:34560
	s_waitcnt lgkmcnt(5)
	v_mfma_f32_16x16x32_bf16 v[24:27], v[160:163], v[148:151], v[24:27]
	ds_read_b128 v[98:101], v80 offset:64
	s_waitcnt lgkmcnt(5)
	v_mfma_f32_16x16x32_bf16 v[20:23], v[164:167], v[148:151], v[20:23]
	ds_read_b128 v[160:163], v78 offset:18496
	s_waitcnt lgkmcnt(5)
	v_mfma_f32_16x16x32_bf16 v[86:89], v[168:171], v[148:151], v[16:19]
	ds_read_b128 v[164:167], v78 offset:20800
	s_waitcnt lgkmcnt(5)
	v_mfma_f32_16x16x32_bf16 v[90:93], v[172:175], v[148:151], v[12:15]
	ds_read_b128 v[168:171], v78 offset:23104
	s_waitcnt lgkmcnt(5)
	v_mfma_f32_16x16x32_bf16 v[94:97], v[152:155], v[148:151], v[8:11]
	ds_read_b128 v[152:155], v78 offset:25408
	s_waitcnt lgkmcnt(5)
	v_mfma_f32_16x16x32_bf16 v[82:85], v[156:159], v[148:151], v[4:7]
	s_waitcnt lgkmcnt(3)
	v_mfma_f32_16x16x32_bf16 v[4:7], v[160:163], v[98:101], v[64:67]
	s_nop 2
	ds_read_b128 v[64:67], v78 offset:34624
	s_waitcnt lgkmcnt(3)
	v_mfma_f32_16x16x32_bf16 v[8:11], v[164:167], v[98:101], v[28:31]
	s_nop 2
	ds_read_b128 v[28:31], v78 offset:32320
	s_waitcnt lgkmcnt(3)
	v_mfma_f32_16x16x32_bf16 v[12:15], v[168:171], v[98:101], v[24:27]
	s_nop 2
	ds_read_b128 v[24:27], v78 offset:30016
	ds_read_b128 v[148:151], v78 offset:27712
	s_waitcnt lgkmcnt(4)
	v_mfma_f32_16x16x32_bf16 v[16:19], v[152:155], v[98:101], v[20:23]
	s_waitcnt lgkmcnt(0)
	v_mfma_f32_16x16x32_bf16 v[20:23], v[148:151], v[98:101], v[86:89]
	s_waitcnt lgkmcnt(0)
	s_and_b64 vcc, exec, s[0:1]
	s_cbranch_vccnz .Lsgl_old_1
	s_waitcnt vmcnt(4)
	ds_write_b128 v81, v[40:43] offset:36864
	ds_write_b128 v81, v[44:47] offset:46080
	ds_write_b128 v81, v[56:59] offset:55296
	ds_write_b128 v81, v[60:63] offset:64512
	s_branch .Lsgl_join_1

.Lsgl_join_1:
	s_cmp_gt_u32 s8, 12
	s_waitcnt lgkmcnt(0)
	s_barrier
	v_mfma_f32_16x16x32_bf16 v[24:27], v[24:27], v[98:101], v[90:93]
	v_mfma_f32_16x16x32_bf16 v[28:31], v[28:31], v[98:101], v[94:97]
	v_mfma_f32_16x16x32_bf16 v[64:67], v[64:67], v[98:101], v[82:85]
	s_cbranch_scc1 .LBB0_906
	v_add_co_u32_e32 v40, vcc, 0x11400000, v76
	s_nop 1
	v_addc_co_u32_e32 v41, vcc, 0, v77, vcc
	v_add_co_u32_e32 v44, vcc, 0x11420000, v76
	s_nop 1
	v_addc_co_u32_e32 v45, vcc, 0, v77, vcc
	v_add_co_u32_e32 v56, vcc, 0x400000, v74
	global_load_dwordx4 v[40:43], v[40:41], off offset:384
	s_nop 0
	global_load_dwordx4 v[44:47], v[44:45], off offset:384
	v_addc_co_u32_e32 v57, vcc, 0, v75, vcc
	v_add_co_u32_e32 v60, vcc, 0x420000, v74
	s_nop 1
	v_addc_co_u32_e32 v61, vcc, 0, v75, vcc
	global_load_dwordx4 v[56:59], v[56:57], off offset:384
	s_nop 0
	global_load_dwordx4 v[60:63], v[60:61], off offset:384
.LBB0_906:
	s_andn2_b64 vcc, exec, s[4:5]
	ds_read_b128 v[148:151], v80 offset:36864
	ds_read_b128 v[152:155], v78 offset:55296
	ds_read_b128 v[156:159], v78 offset:57600
	ds_read_b128 v[160:163], v78 offset:59904
	ds_read_b128 v[164:167], v78 offset:62208
	ds_read_b128 v[168:171], v78 offset:64512
	ds_read_b128 v[172:175], v79 offset:11520
	s_waitcnt lgkmcnt(5)
	v_mfma_f32_16x16x32_bf16 v[4:7], v[152:155], v[148:151], v[4:7]
	ds_read_b128 v[152:155], v79 offset:13824
	s_waitcnt lgkmcnt(5)
	v_mfma_f32_16x16x32_bf16 v[8:11], v[156:159], v[148:151], v[8:11]
	ds_read_b128 v[156:159], v79 offset:16128
	s_waitcnt lgkmcnt(5)
	v_mfma_f32_16x16x32_bf16 v[12:15], v[160:163], v[148:151], v[12:15]
	ds_read_b128 v[94:97], v80 offset:36928
	s_waitcnt lgkmcnt(5)
	v_mfma_f32_16x16x32_bf16 v[16:19], v[164:167], v[148:151], v[16:19]
	ds_read_b128 v[160:163], v78 offset:55360
	s_waitcnt lgkmcnt(5)
	v_mfma_f32_16x16x32_bf16 v[82:85], v[168:171], v[148:151], v[20:23]
	ds_read_b128 v[164:167], v78 offset:57664
	s_waitcnt lgkmcnt(5)
	v_mfma_f32_16x16x32_bf16 v[86:89], v[172:175], v[148:151], v[24:27]
	ds_read_b128 v[168:171], v78 offset:59968
	s_waitcnt lgkmcnt(5)
	v_mfma_f32_16x16x32_bf16 v[90:93], v[152:155], v[148:151], v[28:31]
	ds_read_b128 v[152:155], v78 offset:62272
	s_waitcnt lgkmcnt(5)
	v_mfma_f32_16x16x32_bf16 v[74:77], v[156:159], v[148:151], v[64:67]
	ds_read_b128 v[148:151], v78 offset:64576
	ds_read_b128 v[156:159], v79 offset:11584
	s_waitcnt lgkmcnt(5)
	v_mfma_f32_16x16x32_bf16 v[64:67], v[160:163], v[94:97], v[4:7]
	ds_read_b128 v[160:163], v79 offset:13888
	s_waitcnt lgkmcnt(5)
	v_mfma_f32_16x16x32_bf16 v[28:31], v[164:167], v[94:97], v[8:11]
	ds_read_b128 v[164:167], v79 offset:16192
	s_waitcnt lgkmcnt(5)
	v_mfma_f32_16x16x32_bf16 v[24:27], v[168:171], v[94:97], v[12:15]
	s_waitcnt lgkmcnt(4)
	v_mfma_f32_16x16x32_bf16 v[20:23], v[152:155], v[94:97], v[16:19]
	s_waitcnt lgkmcnt(3)
	v_mfma_f32_16x16x32_bf16 v[16:19], v[148:151], v[94:97], v[82:85]
	s_waitcnt lgkmcnt(2)
	v_mfma_f32_16x16x32_bf16 v[12:15], v[156:159], v[94:97], v[86:89]
	s_waitcnt lgkmcnt(1)
	v_mfma_f32_16x16x32_bf16 v[8:11], v[160:163], v[94:97], v[90:93]
	s_waitcnt lgkmcnt(0)
	v_mfma_f32_16x16x32_bf16 v[4:7], v[164:167], v[94:97], v[74:77]
	s_waitcnt lgkmcnt(0)
	s_cbranch_vccnz .LBB0_901
	s_waitcnt vmcnt(4)
	ds_write_b128 v81, v[32:35]
	ds_write_b128 v81, v[36:39] offset:9216
	ds_write_b128 v81, v[48:51] offset:18432
	ds_write_b128 v81, v[52:55] offset:27648
	s_branch .LBB0_901

.LBB0_2527:
	v_add_u32_e32 v166, 0, v126
	s_cmp_gt_u32 s17, 12
	ds_read_b128 v[168:171], v133
	ds_read_b128 v[172:175], v166 offset:18432
	ds_read_b128 v[176:179], v166 offset:20736
	ds_read_b128 v[180:183], v166 offset:23040
	ds_read_b128 v[184:187], v166 offset:25344
	ds_read_b128 v[188:191], v166 offset:27648
	ds_read_b128 v[192:195], v166 offset:29952
	s_waitcnt lgkmcnt(5)
	v_mfma_f32_16x16x32_bf16 v[138:141], v[172:175], v[168:171], v[108:111]
	ds_read_b128 v[172:175], v166 offset:32256
	s_waitcnt lgkmcnt(5)
	v_mfma_f32_16x16x32_bf16 v[112:115], v[176:179], v[168:171], v[112:115]
	ds_read_b128 v[176:179], v166 offset:34560
	s_waitcnt lgkmcnt(5)
	v_mfma_f32_16x16x32_bf16 v[104:107], v[180:183], v[168:171], v[104:107]
	ds_read_b128 v[180:183], v166 offset:36864
	s_waitcnt lgkmcnt(5)
	v_mfma_f32_16x16x32_bf16 v[142:145], v[184:187], v[168:171], v[100:103]
	ds_read_b128 v[184:187], v166 offset:39168
	s_waitcnt lgkmcnt(5)
	v_mfma_f32_16x16x32_bf16 v[96:99], v[188:191], v[168:171], v[96:99]
	ds_read_b128 v[188:191], v166 offset:41472
	s_waitcnt lgkmcnt(5)
	v_mfma_f32_16x16x32_bf16 v[146:149], v[192:195], v[168:171], v[92:95]
	ds_read_b128 v[192:195], v166 offset:43776
	s_waitcnt lgkmcnt(5)
	v_mfma_f32_16x16x32_bf16 v[88:91], v[172:175], v[168:171], v[88:91]
	ds_read_b128 v[172:175], v166 offset:46080
	s_waitcnt lgkmcnt(5)
	v_mfma_f32_16x16x32_bf16 v[150:153], v[176:179], v[168:171], v[84:87]
	ds_read_b128 v[176:179], v166 offset:48384
	s_waitcnt lgkmcnt(5)
	v_mfma_f32_16x16x32_bf16 v[154:157], v[180:183], v[168:171], v[80:83]
	ds_read_b128 v[180:183], v166 offset:50688
	s_waitcnt lgkmcnt(5)
	v_mfma_f32_16x16x32_bf16 v[158:161], v[184:187], v[168:171], v[76:79]
	ds_read_b128 v[184:187], v166 offset:52992
	s_waitcnt lgkmcnt(5)
	v_mfma_f32_16x16x32_bf16 v[162:165], v[188:191], v[168:171], v[72:75]
	ds_read_b128 v[134:137], v133 offset:64
	s_waitcnt lgkmcnt(5)
	v_mfma_f32_16x16x32_bf16 v[108:111], v[192:195], v[168:171], v[68:71]
	ds_read_b128 v[188:191], v166 offset:18496
	s_waitcnt lgkmcnt(5)
	v_mfma_f32_16x16x32_bf16 v[100:103], v[172:175], v[168:171], v[64:67]
	ds_read_b128 v[172:175], v166 offset:20800
	s_waitcnt lgkmcnt(5)
	v_mfma_f32_16x16x32_bf16 v[92:95], v[176:179], v[168:171], v[60:63]
	ds_read_b128 v[176:179], v166 offset:23104
	s_waitcnt lgkmcnt(5)
	v_mfma_f32_16x16x32_bf16 v[84:87], v[180:183], v[168:171], v[56:59]
	ds_read_b128 v[64:67], v166 offset:25408
	s_waitcnt lgkmcnt(5)
	v_mfma_f32_16x16x32_bf16 v[76:79], v[184:187], v[168:171], v[52:55]
	ds_read_b128 v[168:171], v166 offset:43840
	ds_read_b128 v[180:183], v166 offset:27712
	s_waitcnt lgkmcnt(5)
	v_mfma_f32_16x16x32_bf16 v[52:55], v[188:191], v[134:137], v[138:141]
	ds_read_b128 v[184:187], v166 offset:46144
	ds_read_b128 v[188:191], v166 offset:32320
	ds_read_b128 v[72:75], v166 offset:30016
	ds_read_b128 v[192:195], v166 offset:48448
	s_waitcnt lgkmcnt(5)
	v_mfma_f32_16x16x32_bf16 v[108:111], v[168:171], v[134:137], v[108:111]
	ds_read_b128 v[168:171], v166 offset:50752
	s_waitcnt lgkmcnt(4)
	v_mfma_f32_16x16x32_bf16 v[100:103], v[184:187], v[134:137], v[100:103]
	s_waitcnt lgkmcnt(1)
	v_mfma_f32_16x16x32_bf16 v[92:95], v[192:195], v[134:137], v[92:95]
	s_waitcnt lgkmcnt(9)
	v_mfma_f32_16x16x32_bf16 v[56:59], v[172:175], v[134:137], v[112:115]
	s_waitcnt lgkmcnt(8)
	v_mfma_f32_16x16x32_bf16 v[60:63], v[176:179], v[134:137], v[104:107]
	s_waitcnt lgkmcnt(5)
	v_mfma_f32_16x16x32_bf16 v[68:71], v[180:183], v[134:137], v[96:99]
	ds_read_b128 v[112:115], v166 offset:41536
	ds_read_b128 v[104:107], v166 offset:39232
	s_waitcnt lgkmcnt(5)
	v_mfma_f32_16x16x32_bf16 v[80:83], v[188:191], v[134:137], v[88:91]
	ds_read_b128 v[96:99], v166 offset:36928
	s_nop 2
	ds_read_b128 v[88:91], v166 offset:34624
	s_waitcnt lgkmcnt(4)
	v_mfma_f32_16x16x32_bf16 v[84:87], v[168:171], v[134:137], v[84:87]
	s_waitcnt lgkmcnt(4)
	ds_read_b128 v[138:141], v166 offset:53056
	s_and_b64 vcc, exec, s[4:5]
	s_cbranch_vccnz .Lsgl_old_2
	s_waitcnt vmcnt(6)
	ds_write_b128 v128, v[28:31] offset:55296
	ds_write_b128 v128, v[32:35] offset:64512
	ds_write_b128 v129, v[36:39]
	ds_write_b128 v130, v[40:43]
	ds_write_b128 v131, v[44:47]
	ds_write_b128 v132, v[48:51]
	s_branch .Lsgl_join_2
.Lsgl_old_2:
	s_waitcnt vmcnt(4)
	ds_write_b128 v128, v[28:31] offset:55296
	s_waitcnt vmcnt(3)
	ds_write_b128 v128, v[32:35] offset:64512
	ds_write_b128 v129, v[36:39]
	s_waitcnt vmcnt(2)
	ds_write_b128 v130, v[40:43]
	s_waitcnt vmcnt(1)
	ds_write_b128 v131, v[44:47]
	s_waitcnt vmcnt(0)
	ds_write_b128 v132, v[48:51]
.Lsgl_join_2:
	s_cmp_gt_u32 s17, 12
	s_waitcnt lgkmcnt(0)
	v_mfma_f32_16x16x32_bf16 v[64:67], v[64:67], v[134:137], v[142:145]
	s_barrier
	v_mfma_f32_16x16x32_bf16 v[72:75], v[72:75], v[134:137], v[146:149]
	s_waitcnt lgkmcnt(7)
	v_mfma_f32_16x16x32_bf16 v[88:91], v[88:91], v[134:137], v[150:153]
	v_mfma_f32_16x16x32_bf16 v[96:99], v[96:99], v[134:137], v[154:157]
	v_mfma_f32_16x16x32_bf16 v[104:107], v[104:107], v[134:137], v[158:161]
	v_mfma_f32_16x16x32_bf16 v[112:115], v[112:115], v[134:137], v[162:165]
	s_waitcnt lgkmcnt(6)
	v_mfma_f32_16x16x32_bf16 v[76:79], v[138:141], v[134:137], v[76:79]
	s_cbranch_scc1 .LBB0_2529
	v_add_co_u32_e32 v28, vcc, 0x11400000, v124
	s_nop 1
	v_addc_co_u32_e32 v29, vcc, 0, v125, vcc
	v_add_co_u32_e32 v32, vcc, 0x11420000, v124
	s_nop 1
	v_addc_co_u32_e32 v33, vcc, 0, v125, vcc
	v_add_co_u32_e32 v36, vcc, 0xe00000, v122
	global_load_dwordx4 v[28:31], v[28:29], off offset:384
	s_nop 0
	global_load_dwordx4 v[32:35], v[32:33], off offset:384
	v_addc_co_u32_e32 v37, vcc, 0, v123, vcc
	v_add_co_u32_e32 v40, vcc, 0xe20000, v122
	s_nop 1
	v_addc_co_u32_e32 v41, vcc, 0, v123, vcc
	v_add_co_u32_e32 v44, vcc, 0xe40000, v122
	global_load_dwordx4 v[36:39], v[36:37], off offset:384
	s_nop 0
	global_load_dwordx4 v[40:43], v[40:41], off offset:384
	v_addc_co_u32_e32 v45, vcc, 0, v123, vcc
	v_add_co_u32_e32 v48, vcc, 0xe60000, v122
	s_nop 1
	v_addc_co_u32_e32 v49, vcc, 0, v123, vcc
	global_load_dwordx4 v[44:47], v[44:45], off offset:384
	s_nop 0
	global_load_dwordx4 v[48:51], v[48:49], off offset:384
.LBB0_2529:
	v_add_u32_e32 v170, 0, v127
	s_add_i32 s18, 0, 0xd800
	v_add_u32_e32 v171, s18, v127
	s_andn2_b64 vcc, exec, s[12:13]
	ds_read_b128 v[172:175], v133 offset:55296
	ds_read_b128 v[176:179], v170 offset:55296
	ds_read_b128 v[180:183], v170 offset:57600
	ds_read_b128 v[184:187], v170 offset:59904
	ds_read_b128 v[188:191], v170 offset:62208
	ds_read_b128 v[192:195], v170 offset:64512
	ds_read_b128 v[196:199], v171 offset:11520
	s_waitcnt lgkmcnt(5)
	v_mfma_f32_16x16x32_bf16 v[134:137], v[176:179], v[172:175], v[52:55]
	ds_read_b128 v[176:179], v171 offset:13824
	s_waitcnt lgkmcnt(5)
	v_mfma_f32_16x16x32_bf16 v[138:141], v[180:183], v[172:175], v[56:59]
	ds_read_b128 v[180:183], v171 offset:16128
	s_waitcnt lgkmcnt(5)
	v_mfma_f32_16x16x32_bf16 v[142:145], v[184:187], v[172:175], v[60:63]
	ds_read_b128 v[184:187], v171 offset:18432
	s_waitcnt lgkmcnt(5)
	v_mfma_f32_16x16x32_bf16 v[146:149], v[188:191], v[172:175], v[64:67]
	ds_read_b128 v[188:191], v171 offset:20736
	s_waitcnt lgkmcnt(5)
	v_mfma_f32_16x16x32_bf16 v[150:153], v[192:195], v[172:175], v[68:71]
	ds_read_b128 v[192:195], v171 offset:23040
	s_waitcnt lgkmcnt(5)
	v_mfma_f32_16x16x32_bf16 v[154:157], v[196:199], v[172:175], v[72:75]
	ds_read_b128 v[196:199], v171 offset:25344
	s_waitcnt lgkmcnt(5)
	v_mfma_f32_16x16x32_bf16 v[80:83], v[176:179], v[172:175], v[80:83]
	ds_read_b128 v[176:179], v171 offset:27648
	s_waitcnt lgkmcnt(5)
	v_mfma_f32_16x16x32_bf16 v[158:161], v[180:183], v[172:175], v[88:91]
	ds_read_b128 v[180:183], v171 offset:29952
	s_waitcnt lgkmcnt(5)
	v_mfma_f32_16x16x32_bf16 v[162:165], v[184:187], v[172:175], v[96:99]
	ds_read_b128 v[184:187], v171 offset:32256
	s_waitcnt lgkmcnt(5)
	v_mfma_f32_16x16x32_bf16 v[166:169], v[188:191], v[172:175], v[104:107]
	ds_read_b128 v[188:191], v171 offset:34560
	s_waitcnt lgkmcnt(5)
	v_mfma_f32_16x16x32_bf16 v[72:75], v[192:195], v[172:175], v[112:115]
	ds_read_b128 v[192:195], v133 offset:55360
	s_waitcnt lgkmcnt(5)
	v_mfma_f32_16x16x32_bf16 v[68:71], v[196:199], v[172:175], v[108:111]
	ds_read_b128 v[196:199], v170 offset:55360
	s_waitcnt lgkmcnt(5)
	v_mfma_f32_16x16x32_bf16 v[64:67], v[176:179], v[172:175], v[100:103]
	ds_read_b128 v[176:179], v170 offset:57664
	s_waitcnt lgkmcnt(5)
	v_mfma_f32_16x16x32_bf16 v[60:63], v[180:183], v[172:175], v[92:95]
	ds_read_b128 v[180:183], v171 offset:23104
	s_waitcnt lgkmcnt(5)
	v_mfma_f32_16x16x32_bf16 v[56:59], v[184:187], v[172:175], v[84:87]
	ds_read_b128 v[184:187], v171 offset:25408
	s_waitcnt lgkmcnt(5)
	v_mfma_f32_16x16x32_bf16 v[52:55], v[188:191], v[172:175], v[76:79]
	ds_read_b128 v[172:175], v171 offset:27712
	ds_read_b128 v[188:191], v171 offset:30016
	s_waitcnt lgkmcnt(5)
	v_mfma_f32_16x16x32_bf16 v[108:111], v[196:199], v[192:195], v[134:137]
	ds_read_b128 v[196:199], v171 offset:32320
	ds_read_b128 v[200:203], v171 offset:34624
	s_waitcnt lgkmcnt(5)
	v_mfma_f32_16x16x32_bf16 v[72:75], v[180:183], v[192:195], v[72:75]
	ds_read_b128 v[180:183], v170 offset:59968
	s_waitcnt lgkmcnt(5)
	v_mfma_f32_16x16x32_bf16 v[68:71], v[184:187], v[192:195], v[68:71]
	ds_read_b128 v[184:187], v170 offset:62272
	s_waitcnt lgkmcnt(5)
	v_mfma_f32_16x16x32_bf16 v[64:67], v[172:175], v[192:195], v[64:67]
	ds_read_b128 v[172:175], v170 offset:64576
	s_waitcnt lgkmcnt(5)
	v_mfma_f32_16x16x32_bf16 v[60:63], v[188:191], v[192:195], v[60:63]
	ds_read_b128 v[188:191], v171 offset:11584
	s_waitcnt lgkmcnt(5)
	v_mfma_f32_16x16x32_bf16 v[56:59], v[196:199], v[192:195], v[56:59]
	s_waitcnt lgkmcnt(10)
	v_mfma_f32_16x16x32_bf16 v[112:115], v[176:179], v[192:195], v[138:141]
	ds_read_b128 v[176:179], v171 offset:13888
	ds_read_b128 v[196:199], v171 offset:16192
	s_waitcnt lgkmcnt(5)
	v_mfma_f32_16x16x32_bf16 v[104:107], v[180:183], v[192:195], v[142:145]
	ds_read_b128 v[180:183], v171 offset:18496
	s_waitcnt lgkmcnt(5)
	v_mfma_f32_16x16x32_bf16 v[100:103], v[184:187], v[192:195], v[146:149]
	ds_read_b128 v[184:187], v171 offset:20800
	s_waitcnt lgkmcnt(5)
	v_mfma_f32_16x16x32_bf16 v[96:99], v[172:175], v[192:195], v[150:153]
	s_waitcnt lgkmcnt(4)
	v_mfma_f32_16x16x32_bf16 v[92:95], v[188:191], v[192:195], v[154:157]
	s_waitcnt lgkmcnt(3)
	v_mfma_f32_16x16x32_bf16 v[88:91], v[176:179], v[192:195], v[80:83]
	s_waitcnt lgkmcnt(2)
	v_mfma_f32_16x16x32_bf16 v[84:87], v[196:199], v[192:195], v[158:161]
	s_waitcnt lgkmcnt(1)
	v_mfma_f32_16x16x32_bf16 v[80:83], v[180:183], v[192:195], v[162:165]
	s_waitcnt lgkmcnt(0)
	v_mfma_f32_16x16x32_bf16 v[76:79], v[184:187], v[192:195], v[166:169]
	s_waitcnt lgkmcnt(8)
	v_mfma_f32_16x16x32_bf16 v[52:55], v[200:203], v[192:195], v[52:55]
	s_waitcnt lgkmcnt(0)
	s_cbranch_vccnz .LBB0_2524
	s_waitcnt vmcnt(6)
	ds_write_b128 v128, v[4:7]
	ds_write_b128 v128, v[8:11] offset:9216
	ds_write_b128 v128, v[12:15] offset:18432
	ds_write_b128 v128, v[16:19] offset:27648
	ds_write_b128 v128, v[20:23] offset:36864
	ds_write_b128 v128, v[24:27] offset:46080
	s_branch .LBB0_2524

.LBB0_2551:
	v_add_u32_e32 v166, 0, v126
	s_cmp_gt_u32 s9, 12
	ds_read_b128 v[168:171], v133
	ds_read_b128 v[172:175], v166 offset:18432
	ds_read_b128 v[176:179], v166 offset:20736
	ds_read_b128 v[180:183], v166 offset:23040
	ds_read_b128 v[184:187], v166 offset:25344
	ds_read_b128 v[188:191], v166 offset:27648
	ds_read_b128 v[192:195], v166 offset:29952
	s_waitcnt lgkmcnt(5)
	v_mfma_f32_16x16x32_bf16 v[138:141], v[172:175], v[168:171], v[108:111]
	ds_read_b128 v[172:175], v166 offset:32256
	s_waitcnt lgkmcnt(5)
	v_mfma_f32_16x16x32_bf16 v[112:115], v[176:179], v[168:171], v[112:115]
	ds_read_b128 v[176:179], v166 offset:34560
	s_waitcnt lgkmcnt(5)
	v_mfma_f32_16x16x32_bf16 v[104:107], v[180:183], v[168:171], v[104:107]
	ds_read_b128 v[180:183], v166 offset:36864
	s_waitcnt lgkmcnt(5)
	v_mfma_f32_16x16x32_bf16 v[142:145], v[184:187], v[168:171], v[100:103]
	ds_read_b128 v[184:187], v166 offset:39168
	s_waitcnt lgkmcnt(5)
	v_mfma_f32_16x16x32_bf16 v[96:99], v[188:191], v[168:171], v[96:99]
	ds_read_b128 v[188:191], v166 offset:41472
	s_waitcnt lgkmcnt(5)
	v_mfma_f32_16x16x32_bf16 v[146:149], v[192:195], v[168:171], v[92:95]
	ds_read_b128 v[192:195], v166 offset:43776
	s_waitcnt lgkmcnt(5)
	v_mfma_f32_16x16x32_bf16 v[88:91], v[172:175], v[168:171], v[88:91]
	ds_read_b128 v[172:175], v166 offset:46080
	s_waitcnt lgkmcnt(5)
	v_mfma_f32_16x16x32_bf16 v[150:153], v[176:179], v[168:171], v[84:87]
	ds_read_b128 v[176:179], v166 offset:48384
	s_waitcnt lgkmcnt(5)
	v_mfma_f32_16x16x32_bf16 v[154:157], v[180:183], v[168:171], v[80:83]
	ds_read_b128 v[180:183], v166 offset:50688
	s_waitcnt lgkmcnt(5)
	v_mfma_f32_16x16x32_bf16 v[158:161], v[184:187], v[168:171], v[76:79]
	ds_read_b128 v[184:187], v166 offset:52992
	s_waitcnt lgkmcnt(5)
	v_mfma_f32_16x16x32_bf16 v[162:165], v[188:191], v[168:171], v[72:75]
	ds_read_b128 v[134:137], v133 offset:64
	s_waitcnt lgkmcnt(5)
	v_mfma_f32_16x16x32_bf16 v[108:111], v[192:195], v[168:171], v[68:71]
	ds_read_b128 v[188:191], v166 offset:18496
	s_waitcnt lgkmcnt(5)
	v_mfma_f32_16x16x32_bf16 v[100:103], v[172:175], v[168:171], v[64:67]
	ds_read_b128 v[172:175], v166 offset:20800
	s_waitcnt lgkmcnt(5)
	v_mfma_f32_16x16x32_bf16 v[92:95], v[176:179], v[168:171], v[60:63]
	ds_read_b128 v[176:179], v166 offset:23104
	s_waitcnt lgkmcnt(5)
	v_mfma_f32_16x16x32_bf16 v[84:87], v[180:183], v[168:171], v[56:59]
	ds_read_b128 v[64:67], v166 offset:25408
	s_waitcnt lgkmcnt(5)
	v_mfma_f32_16x16x32_bf16 v[76:79], v[184:187], v[168:171], v[52:55]
	ds_read_b128 v[168:171], v166 offset:43840
	ds_read_b128 v[180:183], v166 offset:27712
	s_waitcnt lgkmcnt(5)
	v_mfma_f32_16x16x32_bf16 v[52:55], v[188:191], v[134:137], v[138:141]
	ds_read_b128 v[184:187], v166 offset:46144
	ds_read_b128 v[188:191], v166 offset:32320
	ds_read_b128 v[72:75], v166 offset:30016
	ds_read_b128 v[192:195], v166 offset:48448
	s_waitcnt lgkmcnt(5)
	v_mfma_f32_16x16x32_bf16 v[108:111], v[168:171], v[134:137], v[108:111]
	ds_read_b128 v[168:171], v166 offset:50752
	s_waitcnt lgkmcnt(4)
	v_mfma_f32_16x16x32_bf16 v[100:103], v[184:187], v[134:137], v[100:103]
	s_waitcnt lgkmcnt(1)
	v_mfma_f32_16x16x32_bf16 v[92:95], v[192:195], v[134:137], v[92:95]
	s_waitcnt lgkmcnt(9)
	v_mfma_f32_16x16x32_bf16 v[56:59], v[172:175], v[134:137], v[112:115]
	s_waitcnt lgkmcnt(8)
	v_mfma_f32_16x16x32_bf16 v[60:63], v[176:179], v[134:137], v[104:107]
	s_waitcnt lgkmcnt(5)
	v_mfma_f32_16x16x32_bf16 v[68:71], v[180:183], v[134:137], v[96:99]
	ds_read_b128 v[112:115], v166 offset:41536
	ds_read_b128 v[104:107], v166 offset:39232
	s_waitcnt lgkmcnt(5)
	v_mfma_f32_16x16x32_bf16 v[80:83], v[188:191], v[134:137], v[88:91]
	ds_read_b128 v[96:99], v166 offset:36928
	s_nop 2
	ds_read_b128 v[88:91], v166 offset:34624
	s_waitcnt lgkmcnt(4)
	v_mfma_f32_16x16x32_bf16 v[84:87], v[168:171], v[134:137], v[84:87]
	s_waitcnt lgkmcnt(4)
	ds_read_b128 v[138:141], v166 offset:53056
	s_and_b64 vcc, exec, s[4:5]
	s_cbranch_vccnz .Lsgl_old_3
	s_waitcnt vmcnt(6)
	ds_write_b128 v128, v[28:31] offset:55296
	ds_write_b128 v128, v[32:35] offset:64512
	ds_write_b128 v129, v[36:39]
	ds_write_b128 v130, v[40:43]
	ds_write_b128 v131, v[44:47]
	ds_write_b128 v132, v[48:51]
	s_branch .Lsgl_join_3

.Lsgl_join_3:
	s_cmp_gt_u32 s9, 12
	s_waitcnt lgkmcnt(0)
	v_mfma_f32_16x16x32_bf16 v[64:67], v[64:67], v[134:137], v[142:145]
	s_barrier
	v_mfma_f32_16x16x32_bf16 v[72:75], v[72:75], v[134:137], v[146:149]
	s_waitcnt lgkmcnt(7)
	v_mfma_f32_16x16x32_bf16 v[88:91], v[88:91], v[134:137], v[150:153]
	v_mfma_f32_16x16x32_bf16 v[96:99], v[96:99], v[134:137], v[154:157]
	v_mfma_f32_16x16x32_bf16 v[104:107], v[104:107], v[134:137], v[158:161]
	v_mfma_f32_16x16x32_bf16 v[112:115], v[112:115], v[134:137], v[162:165]
	s_waitcnt lgkmcnt(6)
	v_mfma_f32_16x16x32_bf16 v[76:79], v[138:141], v[134:137], v[76:79]
	s_cbranch_scc1 .LBB0_2553
	v_add_co_u32_e32 v28, vcc, 0x11400000, v124
	s_nop 1
	v_addc_co_u32_e32 v29, vcc, 0, v125, vcc
	v_add_co_u32_e32 v32, vcc, 0x11420000, v124
	s_nop 1
	v_addc_co_u32_e32 v33, vcc, 0, v125, vcc
	v_add_co_u32_e32 v36, vcc, 0xe00000, v122
	global_load_dwordx4 v[28:31], v[28:29], off offset:384
	s_nop 0
	global_load_dwordx4 v[32:35], v[32:33], off offset:384
	v_addc_co_u32_e32 v37, vcc, 0, v123, vcc
	v_add_co_u32_e32 v40, vcc, 0xe20000, v122
	s_nop 1
	v_addc_co_u32_e32 v41, vcc, 0, v123, vcc
	v_add_co_u32_e32 v44, vcc, 0xe40000, v122
	global_load_dwordx4 v[36:39], v[36:37], off offset:384
	s_nop 0
	global_load_dwordx4 v[40:43], v[40:41], off offset:384
	v_addc_co_u32_e32 v45, vcc, 0, v123, vcc
	v_add_co_u32_e32 v48, vcc, 0xe60000, v122
	s_nop 1
	v_addc_co_u32_e32 v49, vcc, 0, v123, vcc
	global_load_dwordx4 v[44:47], v[44:45], off offset:384
	s_nop 0
	global_load_dwordx4 v[48:51], v[48:49], off offset:384
.LBB0_2553:
	v_add_u32_e32 v170, 0, v127
	s_add_i32 s12, 0, 0xd800
	v_add_u32_e32 v171, s12, v127
	s_andn2_b64 vcc, exec, s[6:7]
	ds_read_b128 v[172:175], v133 offset:55296
	ds_read_b128 v[176:179], v170 offset:55296
	ds_read_b128 v[180:183], v170 offset:57600
	ds_read_b128 v[184:187], v170 offset:59904
	ds_read_b128 v[188:191], v170 offset:62208
	ds_read_b128 v[192:195], v170 offset:64512
	ds_read_b128 v[196:199], v171 offset:11520
	s_waitcnt lgkmcnt(5)
	v_mfma_f32_16x16x32_bf16 v[134:137], v[176:179], v[172:175], v[52:55]
	ds_read_b128 v[176:179], v171 offset:13824
	s_waitcnt lgkmcnt(5)
	v_mfma_f32_16x16x32_bf16 v[138:141], v[180:183], v[172:175], v[56:59]
	ds_read_b128 v[180:183], v171 offset:16128
	s_waitcnt lgkmcnt(5)
	v_mfma_f32_16x16x32_bf16 v[142:145], v[184:187], v[172:175], v[60:63]
	ds_read_b128 v[184:187], v171 offset:18432
	s_waitcnt lgkmcnt(5)
	v_mfma_f32_16x16x32_bf16 v[146:149], v[188:191], v[172:175], v[64:67]
	ds_read_b128 v[188:191], v171 offset:20736
	s_waitcnt lgkmcnt(5)
	v_mfma_f32_16x16x32_bf16 v[150:153], v[192:195], v[172:175], v[68:71]
	ds_read_b128 v[192:195], v171 offset:23040
	s_waitcnt lgkmcnt(5)
	v_mfma_f32_16x16x32_bf16 v[154:157], v[196:199], v[172:175], v[72:75]
	ds_read_b128 v[196:199], v171 offset:25344
	s_waitcnt lgkmcnt(5)
	v_mfma_f32_16x16x32_bf16 v[80:83], v[176:179], v[172:175], v[80:83]
	ds_read_b128 v[176:179], v171 offset:27648
	s_waitcnt lgkmcnt(5)
	v_mfma_f32_16x16x32_bf16 v[158:161], v[180:183], v[172:175], v[88:91]
	ds_read_b128 v[180:183], v171 offset:29952
	s_waitcnt lgkmcnt(5)
	v_mfma_f32_16x16x32_bf16 v[162:165], v[184:187], v[172:175], v[96:99]
	ds_read_b128 v[184:187], v171 offset:32256
	s_waitcnt lgkmcnt(5)
	v_mfma_f32_16x16x32_bf16 v[166:169], v[188:191], v[172:175], v[104:107]
	ds_read_b128 v[188:191], v171 offset:34560
	s_waitcnt lgkmcnt(5)
	v_mfma_f32_16x16x32_bf16 v[72:75], v[192:195], v[172:175], v[112:115]
	ds_read_b128 v[192:195], v133 offset:55360
	s_waitcnt lgkmcnt(5)
	v_mfma_f32_16x16x32_bf16 v[68:71], v[196:199], v[172:175], v[108:111]
	ds_read_b128 v[196:199], v170 offset:55360
	s_waitcnt lgkmcnt(5)
	v_mfma_f32_16x16x32_bf16 v[64:67], v[176:179], v[172:175], v[100:103]
	ds_read_b128 v[176:179], v170 offset:57664
	s_waitcnt lgkmcnt(5)
	v_mfma_f32_16x16x32_bf16 v[60:63], v[180:183], v[172:175], v[92:95]
	ds_read_b128 v[180:183], v171 offset:23104
	s_waitcnt lgkmcnt(5)
	v_mfma_f32_16x16x32_bf16 v[56:59], v[184:187], v[172:175], v[84:87]
	ds_read_b128 v[184:187], v171 offset:25408
	s_waitcnt lgkmcnt(5)
	v_mfma_f32_16x16x32_bf16 v[52:55], v[188:191], v[172:175], v[76:79]
	ds_read_b128 v[172:175], v171 offset:27712
	ds_read_b128 v[188:191], v171 offset:30016
	s_waitcnt lgkmcnt(5)
	v_mfma_f32_16x16x32_bf16 v[108:111], v[196:199], v[192:195], v[134:137]
	ds_read_b128 v[196:199], v171 offset:32320
	ds_read_b128 v[200:203], v171 offset:34624
	s_waitcnt lgkmcnt(5)
	v_mfma_f32_16x16x32_bf16 v[72:75], v[180:183], v[192:195], v[72:75]
	ds_read_b128 v[180:183], v170 offset:59968
	s_waitcnt lgkmcnt(5)
	v_mfma_f32_16x16x32_bf16 v[68:71], v[184:187], v[192:195], v[68:71]
	ds_read_b128 v[184:187], v170 offset:62272
	s_waitcnt lgkmcnt(5)
	v_mfma_f32_16x16x32_bf16 v[64:67], v[172:175], v[192:195], v[64:67]
	ds_read_b128 v[172:175], v170 offset:64576
	s_waitcnt lgkmcnt(5)
	v_mfma_f32_16x16x32_bf16 v[60:63], v[188:191], v[192:195], v[60:63]
	ds_read_b128 v[188:191], v171 offset:11584
	s_waitcnt lgkmcnt(5)
	v_mfma_f32_16x16x32_bf16 v[56:59], v[196:199], v[192:195], v[56:59]
	s_waitcnt lgkmcnt(10)
	v_mfma_f32_16x16x32_bf16 v[112:115], v[176:179], v[192:195], v[138:141]
	ds_read_b128 v[176:179], v171 offset:13888
	ds_read_b128 v[196:199], v171 offset:16192
	s_waitcnt lgkmcnt(5)
	v_mfma_f32_16x16x32_bf16 v[104:107], v[180:183], v[192:195], v[142:145]
	ds_read_b128 v[180:183], v171 offset:18496
	s_waitcnt lgkmcnt(5)
	v_mfma_f32_16x16x32_bf16 v[100:103], v[184:187], v[192:195], v[146:149]
	ds_read_b128 v[184:187], v171 offset:20800
	s_waitcnt lgkmcnt(5)
	v_mfma_f32_16x16x32_bf16 v[96:99], v[172:175], v[192:195], v[150:153]
	s_waitcnt lgkmcnt(4)
	v_mfma_f32_16x16x32_bf16 v[92:95], v[188:191], v[192:195], v[154:157]
	s_waitcnt lgkmcnt(3)
	v_mfma_f32_16x16x32_bf16 v[88:91], v[176:179], v[192:195], v[80:83]
	s_waitcnt lgkmcnt(2)
	v_mfma_f32_16x16x32_bf16 v[84:87], v[196:199], v[192:195], v[158:161]
	s_waitcnt lgkmcnt(1)
	v_mfma_f32_16x16x32_bf16 v[80:83], v[180:183], v[192:195], v[162:165]
	s_waitcnt lgkmcnt(0)
	v_mfma_f32_16x16x32_bf16 v[76:79], v[184:187], v[192:195], v[166:169]
	s_waitcnt lgkmcnt(8)
	v_mfma_f32_16x16x32_bf16 v[52:55], v[200:203], v[192:195], v[52:55]
	s_waitcnt lgkmcnt(0)
	s_cbranch_vccnz .LBB0_2548
	s_waitcnt vmcnt(6)
	ds_write_b128 v128, v[4:7]
	ds_write_b128 v128, v[8:11] offset:9216
	ds_write_b128 v128, v[12:15] offset:18432
	ds_write_b128 v128, v[16:19] offset:27648
	ds_write_b128 v128, v[20:23] offset:36864
	ds_write_b128 v128, v[24:27] offset:46080
	s_branch .LBB0_2548

.LBB0_2632:
	v_add_u32_e32 v94, 0, v79
	s_cmp_gt_u32 s17, 28
	ds_read_b128 v[96:99], v85
	ds_read_b128 v[100:103], v94 offset:34816
	ds_read_b128 v[104:107], v94 offset:39168
	ds_read_b128 v[108:111], v94 offset:43520
	ds_read_b128 v[112:115], v94 offset:47872
	ds_read_b128 v[116:119], v85 offset:64
	ds_read_b128 v[120:123], v94 offset:34880
	s_waitcnt lgkmcnt(5)
	v_mfma_f32_16x16x32_bf16 v[52:55], v[100:103], v[96:99], v[52:55]
	ds_read_b128 v[100:103], v94 offset:39232
	s_waitcnt lgkmcnt(5)
	v_mfma_f32_16x16x32_bf16 v[64:67], v[104:107], v[96:99], v[64:67]
	ds_read_b128 v[104:107], v94 offset:43584
	s_waitcnt lgkmcnt(5)
	v_mfma_f32_16x16x32_bf16 v[60:63], v[108:111], v[96:99], v[60:63]
	ds_read_b128 v[108:111], v94 offset:47936
	s_waitcnt lgkmcnt(5)
	v_mfma_f32_16x16x32_bf16 v[56:59], v[112:115], v[96:99], v[56:59]
	ds_read_b128 v[96:99], v85 offset:128
	ds_read_b128 v[112:115], v94 offset:34944
	s_waitcnt lgkmcnt(5)
	v_mfma_f32_16x16x32_bf16 v[52:55], v[120:123], v[116:119], v[52:55]
	ds_read_b128 v[120:123], v94 offset:39296
	s_waitcnt lgkmcnt(5)
	v_mfma_f32_16x16x32_bf16 v[64:67], v[100:103], v[116:119], v[64:67]
	ds_read_b128 v[100:103], v94 offset:43648
	s_waitcnt lgkmcnt(5)
	v_mfma_f32_16x16x32_bf16 v[60:63], v[104:107], v[116:119], v[60:63]
	ds_read_b128 v[104:107], v94 offset:48000
	s_waitcnt lgkmcnt(5)
	v_mfma_f32_16x16x32_bf16 v[56:59], v[108:111], v[116:119], v[56:59]
	ds_read_b128 v[90:93], v85 offset:192
	ds_read_b128 v[108:111], v94 offset:35008
	s_waitcnt lgkmcnt(5)
	v_mfma_f32_16x16x32_bf16 v[52:55], v[112:115], v[96:99], v[52:55]
	ds_read_b128 v[112:115], v94 offset:39360
	s_waitcnt lgkmcnt(5)
	v_mfma_f32_16x16x32_bf16 v[64:67], v[120:123], v[96:99], v[64:67]
	ds_read_b128 v[116:119], v94 offset:43712
	s_waitcnt lgkmcnt(5)
	v_mfma_f32_16x16x32_bf16 v[60:63], v[100:103], v[96:99], v[60:63]
	s_waitcnt lgkmcnt(4)
	v_mfma_f32_16x16x32_bf16 v[86:89], v[104:107], v[96:99], v[56:59]
	s_waitcnt lgkmcnt(2)
	v_mfma_f32_16x16x32_bf16 v[52:55], v[108:111], v[90:93], v[52:55]
	s_waitcnt lgkmcnt(1)
	v_mfma_f32_16x16x32_bf16 v[56:59], v[112:115], v[90:93], v[64:67]
	s_waitcnt lgkmcnt(0)
	v_mfma_f32_16x16x32_bf16 v[60:63], v[116:119], v[90:93], v[60:63]
	s_waitcnt lgkmcnt(0)
	ds_read_b128 v[64:67], v94 offset:48064
	s_and_b64 vcc, exec, s[4:5]
	s_cbranch_vccnz .Lsgl_old_4
	s_waitcnt vmcnt(6)
	ds_write_b128 v80, v[12:15] offset:52224
	ds_write_b128 v80, v[16:19] offset:60928
	ds_write_b128 v81, v[28:31] offset:17408
	ds_write_b128 v81, v[32:35] offset:26112
	ds_write_b128 v82, v[44:47]
	ds_write_b128 v83, v[48:51]
	s_branch .Lsgl_join_4
.Lsgl_old_4:
	s_waitcnt vmcnt(5)
	ds_write_b128 v80, v[12:15] offset:52224
	s_waitcnt vmcnt(4)
	ds_write_b128 v80, v[16:19] offset:60928
	s_waitcnt vmcnt(3)
	ds_write_b128 v81, v[28:31] offset:17408
	s_waitcnt vmcnt(2)
	ds_write_b128 v81, v[32:35] offset:26112
	s_waitcnt vmcnt(1)
	ds_write_b128 v82, v[44:47]
	s_waitcnt vmcnt(0)
	ds_write_b128 v83, v[48:51]
.Lsgl_join_4:
	s_cmp_gt_u32 s17, 28
	s_waitcnt lgkmcnt(0)
	s_waitcnt lgkmcnt(6)
	v_mfma_f32_16x16x32_bf16 v[64:67], v[64:67], v[90:93], v[86:89]
	s_barrier
	s_cbranch_scc1 .LBB0_2634
	v_add_co_u32_e32 v12, vcc, 0x31800000, v76
	s_nop 1
	v_addc_co_u32_e32 v13, vcc, 0, v77, vcc
	v_add_co_u32_e32 v16, vcc, 0x31840000, v76
	s_nop 1
	v_addc_co_u32_e32 v17, vcc, 0, v77, vcc
	v_add_co_u32_e32 v28, vcc, 0x31880000, v76
	global_load_dwordx4 v[12:15], v[12:13], off offset:768
	s_nop 0
	global_load_dwordx4 v[16:19], v[16:17], off offset:768
	v_addc_co_u32_e32 v29, vcc, 0, v77, vcc
	v_add_co_u32_e32 v32, vcc, 0x318c0000, v76
	s_nop 1
	v_addc_co_u32_e32 v33, vcc, 0, v77, vcc
	v_add_co_u32_e32 v44, vcc, 0x1600000, v74
	global_load_dwordx4 v[28:31], v[28:29], off offset:768
	s_nop 0
	global_load_dwordx4 v[32:35], v[32:33], off offset:768
	v_addc_co_u32_e32 v45, vcc, 0, v75, vcc
	v_add_co_u32_e32 v48, vcc, 0x1640000, v74
	s_nop 1
	v_addc_co_u32_e32 v49, vcc, 0, v75, vcc
	global_load_dwordx4 v[44:47], v[44:45], off offset:768
	s_nop 0
	global_load_dwordx4 v[48:51], v[48:49], off offset:768
.LBB0_2634:
	s_andn2_b64 vcc, exec, s[6:7]
	ds_read_b128 v[90:93], v85 offset:52224
	ds_read_b128 v[94:97], v84 offset:52224
	ds_read_b128 v[98:101], v84 offset:56576
	ds_read_b128 v[102:105], v84 offset:60928
	ds_read_b128 v[106:109], v84 offset:65280
	ds_read_b128 v[110:113], v85 offset:52288
	ds_read_b128 v[114:117], v84 offset:52288
	s_waitcnt lgkmcnt(5)
	v_mfma_f32_16x16x32_bf16 v[52:55], v[94:97], v[90:93], v[52:55]
	ds_read_b128 v[94:97], v84 offset:56640
	s_waitcnt lgkmcnt(5)
	v_mfma_f32_16x16x32_bf16 v[56:59], v[98:101], v[90:93], v[56:59]
	ds_read_b128 v[98:101], v84 offset:60992
	s_waitcnt lgkmcnt(5)
	v_mfma_f32_16x16x32_bf16 v[60:63], v[102:105], v[90:93], v[60:63]
	ds_read_b128 v[102:105], v84 offset:65344
	s_waitcnt lgkmcnt(5)
	v_mfma_f32_16x16x32_bf16 v[64:67], v[106:109], v[90:93], v[64:67]
	ds_read_b128 v[90:93], v85 offset:52352
	ds_read_b128 v[106:109], v84 offset:52352
	s_waitcnt lgkmcnt(5)
	v_mfma_f32_16x16x32_bf16 v[52:55], v[114:117], v[110:113], v[52:55]
	ds_read_b128 v[114:117], v84 offset:56704
	s_waitcnt lgkmcnt(5)
	v_mfma_f32_16x16x32_bf16 v[56:59], v[94:97], v[110:113], v[56:59]
	ds_read_b128 v[94:97], v84 offset:61056
	s_waitcnt lgkmcnt(5)
	v_mfma_f32_16x16x32_bf16 v[60:63], v[98:101], v[110:113], v[60:63]
	ds_read_b128 v[98:101], v84 offset:65408
	s_waitcnt lgkmcnt(5)
	v_mfma_f32_16x16x32_bf16 v[64:67], v[102:105], v[110:113], v[64:67]
	ds_read_b128 v[102:105], v85 offset:52416
	ds_read_b128 v[110:113], v84 offset:52416
	s_waitcnt lgkmcnt(5)
	v_mfma_f32_16x16x32_bf16 v[52:55], v[106:109], v[90:93], v[52:55]
	ds_read_b128 v[106:109], v84 offset:56768
	s_waitcnt lgkmcnt(5)
	v_mfma_f32_16x16x32_bf16 v[56:59], v[114:117], v[90:93], v[56:59]
	ds_read_b128 v[114:117], v84 offset:61120
	s_waitcnt lgkmcnt(5)
	v_mfma_f32_16x16x32_bf16 v[60:63], v[94:97], v[90:93], v[60:63]
	ds_read_b128 v[94:97], v84 offset:65472
	s_waitcnt lgkmcnt(5)
	v_mfma_f32_16x16x32_bf16 v[74:77], v[98:101], v[90:93], v[64:67]
	s_waitcnt lgkmcnt(3)
	v_mfma_f32_16x16x32_bf16 v[52:55], v[110:113], v[102:105], v[52:55]
	s_waitcnt lgkmcnt(2)
	v_mfma_f32_16x16x32_bf16 v[64:67], v[106:109], v[102:105], v[56:59]
	s_waitcnt lgkmcnt(1)
	v_mfma_f32_16x16x32_bf16 v[60:63], v[114:117], v[102:105], v[60:63]
	s_waitcnt lgkmcnt(0)
	v_mfma_f32_16x16x32_bf16 v[56:59], v[94:97], v[102:105], v[74:77]
	s_waitcnt lgkmcnt(0)
	s_cbranch_vccnz .LBB0_2629
	s_waitcnt vmcnt(6)
	ds_write_b128 v80, v[4:7]
	ds_write_b128 v80, v[8:11] offset:8704
	ds_write_b128 v80, v[20:23] offset:17408
	ds_write_b128 v80, v[24:27] offset:26112
	ds_write_b128 v80, v[36:39] offset:34816
	ds_write_b128 v80, v[40:43] offset:43520
	s_branch .LBB0_2629

.LBB0_2668:
	v_add_u32_e32 v94, 0, v79
	s_cmp_gt_u32 s10, 28
	ds_read_b128 v[96:99], v85
	ds_read_b128 v[100:103], v94 offset:34816
	ds_read_b128 v[104:107], v94 offset:39168
	ds_read_b128 v[108:111], v94 offset:43520
	ds_read_b128 v[112:115], v94 offset:47872
	ds_read_b128 v[116:119], v85 offset:64
	ds_read_b128 v[120:123], v94 offset:34880
	s_waitcnt lgkmcnt(5)
	v_mfma_f32_16x16x32_bf16 v[52:55], v[100:103], v[96:99], v[52:55]
	ds_read_b128 v[100:103], v94 offset:39232
	s_waitcnt lgkmcnt(5)
	v_mfma_f32_16x16x32_bf16 v[64:67], v[104:107], v[96:99], v[64:67]
	ds_read_b128 v[104:107], v94 offset:43584
	s_waitcnt lgkmcnt(5)
	v_mfma_f32_16x16x32_bf16 v[60:63], v[108:111], v[96:99], v[60:63]
	ds_read_b128 v[108:111], v94 offset:47936
	s_waitcnt lgkmcnt(5)
	v_mfma_f32_16x16x32_bf16 v[56:59], v[112:115], v[96:99], v[56:59]
	ds_read_b128 v[96:99], v85 offset:128
	ds_read_b128 v[112:115], v94 offset:34944
	s_waitcnt lgkmcnt(5)
	v_mfma_f32_16x16x32_bf16 v[52:55], v[120:123], v[116:119], v[52:55]
	ds_read_b128 v[120:123], v94 offset:39296
	s_waitcnt lgkmcnt(5)
	v_mfma_f32_16x16x32_bf16 v[64:67], v[100:103], v[116:119], v[64:67]
	ds_read_b128 v[100:103], v94 offset:43648
	s_waitcnt lgkmcnt(5)
	v_mfma_f32_16x16x32_bf16 v[60:63], v[104:107], v[116:119], v[60:63]
	ds_read_b128 v[104:107], v94 offset:48000
	s_waitcnt lgkmcnt(5)
	v_mfma_f32_16x16x32_bf16 v[56:59], v[108:111], v[116:119], v[56:59]
	ds_read_b128 v[90:93], v85 offset:192
	ds_read_b128 v[108:111], v94 offset:35008
	s_waitcnt lgkmcnt(5)
	v_mfma_f32_16x16x32_bf16 v[52:55], v[112:115], v[96:99], v[52:55]
	ds_read_b128 v[112:115], v94 offset:39360
	s_waitcnt lgkmcnt(5)
	v_mfma_f32_16x16x32_bf16 v[64:67], v[120:123], v[96:99], v[64:67]
	ds_read_b128 v[116:119], v94 offset:43712
	s_waitcnt lgkmcnt(5)
	v_mfma_f32_16x16x32_bf16 v[60:63], v[100:103], v[96:99], v[60:63]
	s_waitcnt lgkmcnt(4)
	v_mfma_f32_16x16x32_bf16 v[86:89], v[104:107], v[96:99], v[56:59]
	s_waitcnt lgkmcnt(2)
	v_mfma_f32_16x16x32_bf16 v[52:55], v[108:111], v[90:93], v[52:55]
	s_waitcnt lgkmcnt(1)
	v_mfma_f32_16x16x32_bf16 v[56:59], v[112:115], v[90:93], v[64:67]
	s_waitcnt lgkmcnt(0)
	v_mfma_f32_16x16x32_bf16 v[60:63], v[116:119], v[90:93], v[60:63]
	s_waitcnt lgkmcnt(0)
	ds_read_b128 v[64:67], v94 offset:48064
	s_and_b64 vcc, exec, s[4:5]
	s_cbranch_vccnz .Lsgl_old_5
	s_waitcnt vmcnt(6)
	ds_write_b128 v80, v[12:15] offset:52224
	ds_write_b128 v80, v[16:19] offset:60928
	ds_write_b128 v81, v[28:31] offset:17408
	ds_write_b128 v81, v[32:35] offset:26112
	ds_write_b128 v82, v[44:47]
	ds_write_b128 v83, v[48:51]
	s_branch .Lsgl_join_5

.Lsgl_join_5:
	s_cmp_gt_u32 s10, 28
	s_waitcnt lgkmcnt(0)
	s_waitcnt lgkmcnt(6)
	v_mfma_f32_16x16x32_bf16 v[64:67], v[64:67], v[90:93], v[86:89]
	s_barrier
	s_cbranch_scc1 .LBB0_2670
	v_add_co_u32_e32 v12, vcc, 0x31800000, v76
	s_nop 1
	v_addc_co_u32_e32 v13, vcc, 0, v77, vcc
	v_add_co_u32_e32 v16, vcc, 0x31840000, v76
	s_nop 1
	v_addc_co_u32_e32 v17, vcc, 0, v77, vcc
	v_add_co_u32_e32 v28, vcc, 0x31880000, v76
	global_load_dwordx4 v[12:15], v[12:13], off offset:768
	s_nop 0
	global_load_dwordx4 v[16:19], v[16:17], off offset:768
	v_addc_co_u32_e32 v29, vcc, 0, v77, vcc
	v_add_co_u32_e32 v32, vcc, 0x318c0000, v76
	s_nop 1
	v_addc_co_u32_e32 v33, vcc, 0, v77, vcc
	v_add_co_u32_e32 v44, vcc, 0x1600000, v74
	global_load_dwordx4 v[28:31], v[28:29], off offset:768
	s_nop 0
	global_load_dwordx4 v[32:35], v[32:33], off offset:768
	v_addc_co_u32_e32 v45, vcc, 0, v75, vcc
	v_add_co_u32_e32 v48, vcc, 0x1640000, v74
	s_nop 1
	v_addc_co_u32_e32 v49, vcc, 0, v75, vcc
	global_load_dwordx4 v[44:47], v[44:45], off offset:768
	s_nop 0
	global_load_dwordx4 v[48:51], v[48:49], off offset:768
